# sc1 (write-through) epilogue stores in in-proj and ffn-up GEMM phases
# baseline (speedup 1.0000x reference)
.LBB0_61:
	v_mul_f32_e32 v147, 0xbfb8aa3b, v116
	v_exp_f32_e32 v147, v147
	v_mul_f32_e32 v146, 0xbfb8aa3b, v124
	v_exp_f32_e32 v146, v146
	s_ashr_i32 s55, s54, 31
	v_add_f32_e32 v147, 1.0, v147
	v_rcp_f32_e32 v148, v147
	v_mul_f32_e32 v147, 0xbfb8aa3b, v125
	v_exp_f32_e32 v147, v147
	v_add_f32_e32 v146, 1.0, v146
	v_rcp_f32_e32 v146, v146
	s_lshl_b64 s[0:1], s[54:55], 8
	v_add_f32_e32 v147, 1.0, v147
	v_rcp_f32_e32 v147, v147
	v_lshl_add_u64 v[144:145], v[136:137], 0, s[0:1]
	v_readlane_b32 s0, v253, 0
	v_readlane_b32 s1, v253, 1
	v_pk_mul_f32 v[124:125], v[124:125], v[146:147]
	s_load_dwordx16 s[4:19], s[0:1], 0xf0
	v_pk_mul_f32 v[120:121], v[124:125], v[120:121]
	v_mul_f32_e32 v124, 0xbfb8aa3b, v117
	v_exp_f32_e32 v124, v124
	s_lshl_b32 s54, s30, 7
	s_ashr_i32 s55, s54, 31
	s_mov_b64 s[20:21], -1
	v_add_f32_e32 v124, 1.0, v124
	v_rcp_f32_e32 v149, v124
	s_nop 0
	v_pk_mul_f32 v[116:117], v[116:117], v[148:149]
	s_nop 0
	v_pk_mul_f32 v[112:113], v[116:117], v[112:113]
	v_mul_f32_e32 v117, 0xbfb8aa3b, v118
	v_exp_f32_e32 v117, v117
	v_mul_f32_e32 v116, 0xbfb8aa3b, v126
	v_exp_f32_e32 v116, v116
	v_add_f32_e32 v117, 1.0, v117
	v_rcp_f32_e32 v124, v117
	v_mul_f32_e32 v117, 0xbfb8aa3b, v127
	v_exp_f32_e32 v117, v117
	v_add_f32_e32 v116, 1.0, v116
	v_rcp_f32_e32 v116, v116
	v_add_f32_e32 v117, 1.0, v117
	v_rcp_f32_e32 v117, v117
	s_nop 0
	v_pk_mul_f32 v[116:117], v[126:127], v[116:117]
	s_nop 0
	v_pk_mul_f32 v[116:117], v[116:117], v[122:123]
	v_mul_f32_e32 v122, 0xbfb8aa3b, v119
	v_exp_f32_e32 v122, v122
	s_nop 0
	v_add_f32_e32 v122, 1.0, v122
	v_rcp_f32_e32 v125, v122
	s_nop 0
	v_pk_mul_f32 v[118:119], v[118:119], v[124:125]
	s_nop 0
	v_pk_mul_f32 v[118:119], v[118:119], v[114:115]
	v_cvt_pk_bf16_f32 v115, v116, v117
	v_cvt_pk_bf16_f32 v116, v112, v113
	s_waitcnt lgkmcnt(0)
	v_mov_b64_e32 v[112:113], s[12:13]
	v_mad_u64_u32 v[112:113], s[0:1], v144, s96, v[112:113]
	v_cvt_pk_bf16_f32 v117, v118, v119
	v_mov_b32_e32 v118, v113
	v_mad_u64_u32 v[118:119], s[0:1], v145, s96, v[118:119]
	v_mov_b32_e32 v113, v118
	v_lshl_add_u64 v[112:113], s[54:55], 1, v[112:113]
	v_lshl_add_u64 v[112:113], v[112:113], 0, s[70:71]
	v_cvt_pk_bf16_f32 v114, v120, v121
	v_lshl_add_u64 v[112:113], v[112:113], 0, v[176:177]
	global_store_dwordx4 v[112:113], v[114:117], off sc1
	s_mov_b32 s0, 0x16000
	s_nop 0
	v_mul_f32_e32 v115, 0xbfb8aa3b, v100
	v_exp_f32_e32 v115, v115
	v_mul_f32_e32 v114, 0xbfb8aa3b, v108
	v_exp_f32_e32 v114, v114
	v_add_f32_e32 v115, 1.0, v115
	v_rcp_f32_e32 v116, v115
	v_mul_f32_e32 v115, 0xbfb8aa3b, v109
	v_exp_f32_e32 v115, v115
	v_add_f32_e32 v114, 1.0, v114
	v_rcp_f32_e32 v114, v114
	v_add_f32_e32 v115, 1.0, v115
	v_rcp_f32_e32 v115, v115
	s_nop 0
	v_pk_mul_f32 v[108:109], v[108:109], v[114:115]
	s_nop 0
	v_pk_mul_f32 v[104:105], v[108:109], v[104:105]
	v_mul_f32_e32 v108, 0xbfb8aa3b, v101
	v_exp_f32_e32 v108, v108
	s_nop 0
	v_add_f32_e32 v108, 1.0, v108
	v_rcp_f32_e32 v117, v108
	s_nop 0
	v_pk_mul_f32 v[100:101], v[100:101], v[116:117]
	s_nop 0
	v_pk_mul_f32 v[100:101], v[100:101], v[96:97]
	v_mul_f32_e32 v97, 0xbfb8aa3b, v102
	v_exp_f32_e32 v97, v97
	v_mul_f32_e32 v96, 0xbfb8aa3b, v110
	v_exp_f32_e32 v96, v96
	v_add_f32_e32 v97, 1.0, v97
	v_rcp_f32_e32 v108, v97
	v_mul_f32_e32 v97, 0xbfb8aa3b, v111
	v_exp_f32_e32 v97, v97
	v_add_f32_e32 v96, 1.0, v96
	v_rcp_f32_e32 v96, v96
	v_add_f32_e32 v97, 1.0, v97
	v_rcp_f32_e32 v97, v97
	s_nop 0
	v_pk_mul_f32 v[96:97], v[110:111], v[96:97]
	s_nop 0
	v_pk_mul_f32 v[106:107], v[96:97], v[106:107]
	v_mul_f32_e32 v96, 0xbfb8aa3b, v103
	v_exp_f32_e32 v96, v96
	s_nop 0
	v_add_f32_e32 v96, 1.0, v96
	v_rcp_f32_e32 v109, v96
	s_nop 0
	v_pk_mul_f32 v[96:97], v[102:103], v[108:109]
	s_nop 0
	v_pk_mul_f32 v[102:103], v[96:97], v[98:99]
	v_cvt_pk_bf16_f32 v98, v100, v101
	v_add_co_u32_e32 v100, vcc, s0, v112
	v_cvt_pk_bf16_f32 v96, v104, v105
	v_cvt_pk_bf16_f32 v97, v106, v107
	v_cvt_pk_bf16_f32 v99, v102, v103
	v_addc_co_u32_e32 v101, vcc, 0, v113, vcc
	global_store_dwordx4 v[100:101], v[96:99], off sc1
	s_mov_b32 s0, 0x2c000
	s_nop 0
	v_mul_f32_e32 v97, 0xbfb8aa3b, v84
	v_exp_f32_e32 v97, v97
	v_mul_f32_e32 v96, 0xbfb8aa3b, v92
	v_exp_f32_e32 v96, v96
	v_add_f32_e32 v97, 1.0, v97
	v_rcp_f32_e32 v98, v97
	v_mul_f32_e32 v97, 0xbfb8aa3b, v93
	v_exp_f32_e32 v97, v97
	v_add_f32_e32 v96, 1.0, v96
	v_rcp_f32_e32 v96, v96
	v_add_f32_e32 v97, 1.0, v97
	v_rcp_f32_e32 v97, v97
	s_nop 0
	v_pk_mul_f32 v[92:93], v[92:93], v[96:97]
	s_nop 0
	v_pk_mul_f32 v[88:89], v[92:93], v[88:89]
	v_mul_f32_e32 v92, 0xbfb8aa3b, v85
	v_exp_f32_e32 v92, v92
	s_nop 0
	v_add_f32_e32 v92, 1.0, v92
	v_rcp_f32_e32 v99, v92
	s_nop 0
	v_pk_mul_f32 v[84:85], v[84:85], v[98:99]
	s_nop 0
	v_pk_mul_f32 v[84:85], v[84:85], v[80:81]
	v_mul_f32_e32 v81, 0xbfb8aa3b, v86
	v_exp_f32_e32 v81, v81
	v_mul_f32_e32 v80, 0xbfb8aa3b, v94
	v_exp_f32_e32 v80, v80
	v_add_f32_e32 v81, 1.0, v81
	v_rcp_f32_e32 v92, v81
	v_mul_f32_e32 v81, 0xbfb8aa3b, v95
	v_exp_f32_e32 v81, v81
	v_add_f32_e32 v80, 1.0, v80
	v_rcp_f32_e32 v80, v80
	v_add_f32_e32 v81, 1.0, v81
	v_rcp_f32_e32 v81, v81
	s_nop 0
	v_pk_mul_f32 v[80:81], v[94:95], v[80:81]
	s_nop 0
	v_pk_mul_f32 v[90:91], v[80:81], v[90:91]
	v_mul_f32_e32 v80, 0xbfb8aa3b, v87
	v_exp_f32_e32 v80, v80
	s_nop 0
	v_add_f32_e32 v80, 1.0, v80
	v_rcp_f32_e32 v93, v80
	s_nop 0
	v_pk_mul_f32 v[80:81], v[86:87], v[92:93]
	s_nop 0
	v_pk_mul_f32 v[86:87], v[80:81], v[82:83]
	v_cvt_pk_bf16_f32 v82, v84, v85
	v_add_co_u32_e32 v84, vcc, s0, v112
	v_cvt_pk_bf16_f32 v80, v88, v89
	v_cvt_pk_bf16_f32 v81, v90, v91
	v_cvt_pk_bf16_f32 v83, v86, v87
	v_addc_co_u32_e32 v85, vcc, 0, v113, vcc
	global_store_dwordx4 v[84:85], v[80:83], off sc1
	s_mov_b32 s0, 0x42000
	s_nop 0
	v_mul_f32_e32 v81, 0xbfb8aa3b, v68
	v_exp_f32_e32 v81, v81
	v_mul_f32_e32 v80, 0xbfb8aa3b, v76
	v_exp_f32_e32 v80, v80
	v_add_f32_e32 v81, 1.0, v81
	v_rcp_f32_e32 v82, v81
	v_mul_f32_e32 v81, 0xbfb8aa3b, v77
	v_exp_f32_e32 v81, v81
	v_add_f32_e32 v80, 1.0, v80
	v_rcp_f32_e32 v80, v80
	v_add_f32_e32 v81, 1.0, v81
	v_rcp_f32_e32 v81, v81
	s_nop 0
	v_pk_mul_f32 v[76:77], v[76:77], v[80:81]
	s_nop 0
	v_pk_mul_f32 v[72:73], v[76:77], v[72:73]
	v_mul_f32_e32 v76, 0xbfb8aa3b, v69
	v_exp_f32_e32 v76, v76
	s_nop 0
	v_add_f32_e32 v76, 1.0, v76
	v_rcp_f32_e32 v83, v76
	s_nop 0
	v_pk_mul_f32 v[68:69], v[68:69], v[82:83]
	s_nop 0
	v_pk_mul_f32 v[68:69], v[68:69], v[64:65]
	v_mul_f32_e32 v65, 0xbfb8aa3b, v70
	v_exp_f32_e32 v65, v65
	v_mul_f32_e32 v64, 0xbfb8aa3b, v78
	v_exp_f32_e32 v64, v64
	v_add_f32_e32 v65, 1.0, v65
	v_rcp_f32_e32 v76, v65
	v_mul_f32_e32 v65, 0xbfb8aa3b, v79
	v_exp_f32_e32 v65, v65
	v_add_f32_e32 v64, 1.0, v64
	v_rcp_f32_e32 v64, v64
	v_add_f32_e32 v65, 1.0, v65
	v_rcp_f32_e32 v65, v65
	s_nop 0
	v_pk_mul_f32 v[64:65], v[78:79], v[64:65]
	s_nop 0
	v_pk_mul_f32 v[74:75], v[64:65], v[74:75]
	v_mul_f32_e32 v64, 0xbfb8aa3b, v71
	v_exp_f32_e32 v64, v64
	s_nop 0
	v_add_f32_e32 v64, 1.0, v64
	v_rcp_f32_e32 v77, v64
	s_nop 0
	v_pk_mul_f32 v[64:65], v[70:71], v[76:77]
	s_nop 0
	v_pk_mul_f32 v[70:71], v[64:65], v[66:67]
	v_cvt_pk_bf16_f32 v66, v68, v69
	v_add_co_u32_e32 v68, vcc, s0, v112
	v_cvt_pk_bf16_f32 v64, v72, v73
	v_cvt_pk_bf16_f32 v65, v74, v75
	v_cvt_pk_bf16_f32 v67, v70, v71
	v_addc_co_u32_e32 v69, vcc, 0, v113, vcc
	global_store_dwordx4 v[68:69], v[64:67], off sc1
	s_mov_b32 s0, 0xb0000
	s_nop 0
	v_mul_f32_e32 v65, 0xbfb8aa3b, v52
	v_exp_f32_e32 v65, v65
	v_mul_f32_e32 v64, 0xbfb8aa3b, v60
	v_exp_f32_e32 v64, v64
	v_add_f32_e32 v65, 1.0, v65
	v_rcp_f32_e32 v66, v65
	v_mul_f32_e32 v65, 0xbfb8aa3b, v61
	v_exp_f32_e32 v65, v65
	v_add_f32_e32 v64, 1.0, v64
	v_rcp_f32_e32 v64, v64
	v_add_f32_e32 v65, 1.0, v65
	v_rcp_f32_e32 v65, v65
	s_nop 0
	v_pk_mul_f32 v[60:61], v[60:61], v[64:65]
	s_nop 0
	v_pk_mul_f32 v[56:57], v[60:61], v[56:57]
	v_mul_f32_e32 v60, 0xbfb8aa3b, v53
	v_exp_f32_e32 v60, v60
	s_nop 0
	v_add_f32_e32 v60, 1.0, v60
	v_rcp_f32_e32 v67, v60
	s_nop 0
	v_pk_mul_f32 v[52:53], v[52:53], v[66:67]
	s_nop 0
	v_pk_mul_f32 v[52:53], v[52:53], v[48:49]
	v_mul_f32_e32 v49, 0xbfb8aa3b, v54
	v_exp_f32_e32 v49, v49
	v_mul_f32_e32 v48, 0xbfb8aa3b, v62
	v_exp_f32_e32 v48, v48
	v_add_f32_e32 v49, 1.0, v49
	v_rcp_f32_e32 v60, v49
	v_mul_f32_e32 v49, 0xbfb8aa3b, v63
	v_exp_f32_e32 v49, v49
	v_add_f32_e32 v48, 1.0, v48
	v_rcp_f32_e32 v48, v48
	v_add_f32_e32 v49, 1.0, v49
	v_rcp_f32_e32 v49, v49
	s_nop 0
	v_pk_mul_f32 v[48:49], v[62:63], v[48:49]
	s_nop 0
	v_pk_mul_f32 v[58:59], v[48:49], v[58:59]
	v_mul_f32_e32 v48, 0xbfb8aa3b, v55
	v_exp_f32_e32 v48, v48
	s_nop 0
	v_add_f32_e32 v48, 1.0, v48
	v_rcp_f32_e32 v61, v48
	s_nop 0
	v_pk_mul_f32 v[48:49], v[54:55], v[60:61]
	s_nop 0
	v_pk_mul_f32 v[54:55], v[48:49], v[50:51]
	v_cvt_pk_bf16_f32 v50, v52, v53
	v_add_co_u32_e32 v52, vcc, s0, v112
	v_cvt_pk_bf16_f32 v48, v56, v57
	v_cvt_pk_bf16_f32 v49, v58, v59
	v_cvt_pk_bf16_f32 v51, v54, v55
	v_addc_co_u32_e32 v53, vcc, 0, v113, vcc
	global_store_dwordx4 v[52:53], v[48:51], off sc1
	s_mov_b32 s0, 0xc6000
	s_nop 0
	v_mul_f32_e32 v49, 0xbfb8aa3b, v36
	v_exp_f32_e32 v49, v49
	v_mul_f32_e32 v48, 0xbfb8aa3b, v44
	v_exp_f32_e32 v48, v48
	v_add_f32_e32 v49, 1.0, v49
	v_rcp_f32_e32 v50, v49
	v_mul_f32_e32 v49, 0xbfb8aa3b, v45
	v_exp_f32_e32 v49, v49
	v_add_f32_e32 v48, 1.0, v48
	v_rcp_f32_e32 v48, v48
	v_add_f32_e32 v49, 1.0, v49
	v_rcp_f32_e32 v49, v49
	s_nop 0
	v_pk_mul_f32 v[44:45], v[44:45], v[48:49]
	s_nop 0
	v_pk_mul_f32 v[40:41], v[44:45], v[40:41]
	v_mul_f32_e32 v44, 0xbfb8aa3b, v37
	v_exp_f32_e32 v44, v44
	s_nop 0
	v_add_f32_e32 v44, 1.0, v44
	v_rcp_f32_e32 v51, v44
	s_nop 0
	v_pk_mul_f32 v[36:37], v[36:37], v[50:51]
	s_nop 0
	v_pk_mul_f32 v[36:37], v[36:37], v[32:33]
	v_mul_f32_e32 v33, 0xbfb8aa3b, v38
	v_exp_f32_e32 v33, v33
	v_mul_f32_e32 v32, 0xbfb8aa3b, v46
	v_exp_f32_e32 v32, v32
	v_add_f32_e32 v33, 1.0, v33
	v_rcp_f32_e32 v44, v33
	v_mul_f32_e32 v33, 0xbfb8aa3b, v47
	v_exp_f32_e32 v33, v33
	v_add_f32_e32 v32, 1.0, v32
	v_rcp_f32_e32 v32, v32
	v_add_f32_e32 v33, 1.0, v33
	v_rcp_f32_e32 v33, v33
	s_nop 0
	v_pk_mul_f32 v[32:33], v[46:47], v[32:33]
	s_nop 0
	v_pk_mul_f32 v[42:43], v[32:33], v[42:43]
	v_mul_f32_e32 v32, 0xbfb8aa3b, v39
	v_exp_f32_e32 v32, v32
	s_nop 0
	v_add_f32_e32 v32, 1.0, v32
	v_rcp_f32_e32 v45, v32
	s_nop 0
	v_pk_mul_f32 v[32:33], v[38:39], v[44:45]
	s_nop 0
	v_pk_mul_f32 v[38:39], v[32:33], v[34:35]
	v_cvt_pk_bf16_f32 v34, v36, v37
	v_add_co_u32_e32 v36, vcc, s0, v112
	v_cvt_pk_bf16_f32 v32, v40, v41
	v_cvt_pk_bf16_f32 v33, v42, v43
	v_cvt_pk_bf16_f32 v35, v38, v39
	v_addc_co_u32_e32 v37, vcc, 0, v113, vcc
	global_store_dwordx4 v[36:37], v[32:35], off sc1
	s_mov_b32 s0, 0xdc000
	s_nop 0
	v_mul_f32_e32 v33, 0xbfb8aa3b, v20
	v_exp_f32_e32 v33, v33
	v_mul_f32_e32 v32, 0xbfb8aa3b, v28
	v_exp_f32_e32 v32, v32
	v_add_f32_e32 v33, 1.0, v33
	v_rcp_f32_e32 v34, v33
	v_mul_f32_e32 v33, 0xbfb8aa3b, v29
	v_exp_f32_e32 v33, v33
	v_add_f32_e32 v32, 1.0, v32
	v_rcp_f32_e32 v32, v32
	v_add_f32_e32 v33, 1.0, v33
	v_rcp_f32_e32 v33, v33
	s_nop 0
	v_pk_mul_f32 v[28:29], v[28:29], v[32:33]
	s_nop 0
	v_pk_mul_f32 v[24:25], v[28:29], v[24:25]
	v_mul_f32_e32 v28, 0xbfb8aa3b, v21
	v_exp_f32_e32 v28, v28
	s_nop 0
	v_add_f32_e32 v28, 1.0, v28
	v_rcp_f32_e32 v35, v28
	s_nop 0
	v_pk_mul_f32 v[20:21], v[20:21], v[34:35]
	s_nop 0
	v_pk_mul_f32 v[20:21], v[20:21], v[16:17]
	v_mul_f32_e32 v17, 0xbfb8aa3b, v22
	v_exp_f32_e32 v17, v17
	v_mul_f32_e32 v16, 0xbfb8aa3b, v30
	v_exp_f32_e32 v16, v16
	v_add_f32_e32 v17, 1.0, v17
	v_rcp_f32_e32 v28, v17
	v_mul_f32_e32 v17, 0xbfb8aa3b, v31
	v_exp_f32_e32 v17, v17
	v_add_f32_e32 v16, 1.0, v16
	v_rcp_f32_e32 v16, v16
	v_add_f32_e32 v17, 1.0, v17
	v_rcp_f32_e32 v17, v17
	s_nop 0
	v_pk_mul_f32 v[16:17], v[30:31], v[16:17]
	s_nop 0
	v_pk_mul_f32 v[26:27], v[16:17], v[26:27]
	v_mul_f32_e32 v16, 0xbfb8aa3b, v23
	v_exp_f32_e32 v16, v16
	s_nop 0
	v_add_f32_e32 v16, 1.0, v16
	v_rcp_f32_e32 v29, v16
	s_nop 0
	v_pk_mul_f32 v[16:17], v[22:23], v[28:29]
	s_nop 0
	v_pk_mul_f32 v[22:23], v[16:17], v[18:19]
	v_cvt_pk_bf16_f32 v18, v20, v21
	v_add_co_u32_e32 v20, vcc, s0, v112
	v_cvt_pk_bf16_f32 v16, v24, v25
	v_cvt_pk_bf16_f32 v17, v26, v27
	v_cvt_pk_bf16_f32 v19, v22, v23
	v_addc_co_u32_e32 v21, vcc, 0, v113, vcc
	global_store_dwordx4 v[20:21], v[16:19], off sc1
	s_nop 1
	v_mul_f32_e32 v17, 0xbfb8aa3b, v4
	v_exp_f32_e32 v17, v17
	v_mul_f32_e32 v16, 0xbfb8aa3b, v12
	v_exp_f32_e32 v16, v16
	v_add_f32_e32 v17, 1.0, v17
	v_rcp_f32_e32 v18, v17
	v_mul_f32_e32 v17, 0xbfb8aa3b, v13
	v_exp_f32_e32 v17, v17
	v_add_f32_e32 v16, 1.0, v16
	v_rcp_f32_e32 v16, v16
	v_add_f32_e32 v17, 1.0, v17
	v_rcp_f32_e32 v17, v17
	s_nop 0
	v_pk_mul_f32 v[12:13], v[12:13], v[16:17]
	s_nop 0
	v_pk_mul_f32 v[8:9], v[12:13], v[8:9]
	v_mul_f32_e32 v12, 0xbfb8aa3b, v5
	v_exp_f32_e32 v12, v12
	s_nop 0
	v_add_f32_e32 v12, 1.0, v12
	v_rcp_f32_e32 v19, v12
	s_nop 0
	v_pk_mul_f32 v[4:5], v[4:5], v[18:19]
	s_nop 0
	v_pk_mul_f32 v[4:5], v[4:5], v[0:1]
	v_mul_f32_e32 v1, 0xbfb8aa3b, v6
	v_exp_f32_e32 v1, v1
	v_mul_f32_e32 v0, 0xbfb8aa3b, v14
	v_exp_f32_e32 v0, v0
	v_add_f32_e32 v1, 1.0, v1
	v_rcp_f32_e32 v12, v1
	v_mul_f32_e32 v1, 0xbfb8aa3b, v15
	v_exp_f32_e32 v1, v1
	v_add_f32_e32 v0, 1.0, v0
	v_rcp_f32_e32 v0, v0
	v_add_f32_e32 v1, 1.0, v1
	v_rcp_f32_e32 v1, v1
	s_nop 0
	v_pk_mul_f32 v[0:1], v[14:15], v[0:1]
	s_nop 0
	v_pk_mul_f32 v[10:11], v[0:1], v[10:11]
	v_mul_f32_e32 v0, 0xbfb8aa3b, v7
	v_exp_f32_e32 v0, v0
	s_nop 0
	v_add_f32_e32 v0, 1.0, v0
	v_rcp_f32_e32 v13, v0
	s_nop 0
	v_pk_mul_f32 v[0:1], v[6:7], v[12:13]
	s_nop 0
	v_pk_mul_f32 v[6:7], v[0:1], v[2:3]
	v_cvt_pk_bf16_f32 v2, v4, v5
	v_add_co_u32_e32 v4, vcc, 0xf2000, v112
	v_cvt_pk_bf16_f32 v0, v8, v9
	s_nop 0
	v_addc_co_u32_e32 v5, vcc, 0, v113, vcc
	v_cvt_pk_bf16_f32 v1, v10, v11
	v_cvt_pk_bf16_f32 v3, v6, v7
	s_andn2_b64 vcc, exec, s[52:53]
	global_store_dwordx4 v[4:5], v[0:3], off sc1
	s_cbranch_vccnz .LBB0_40
	v_readlane_b32 s0, v252, 26
	v_readlane_b32 s1, v252, 27
	s_andn2_b64 vcc, exec, s[0:1]
	s_cbranch_vccnz .LBB0_39
	s_barrier
	s_branch .LBB0_39

.LBB0_648:
	s_cmpk_lt_i32 s60, 0x80
	v_cmp_ne_u32_e32 vcc, 0, v144
	v_readlane_b32 s66, v252, 9
	s_cselect_b64 s[44:45], -1, 0
	v_lshlrev_b32_e32 v176, 1, v136
	v_readlane_b32 s67, v252, 10
	s_cbranch_vccz .LBB0_651
	s_lshl_b32 s0, s60, 8
	s_add_i32 s20, s60, 0x7fff80
	s_lshr_b32 s21, s60, 3
	s_and_b32 s22, s0, 0x700
	s_and_b64 s[0:1], s[44:45], exec
	s_cselect_b32 s0, s21, s20
	s_cselect_b32 s20, s22, 0x800
	s_lshl_b32 s1, s61, 8
	s_lshl_b32 s0, s0, 9
	s_add_i32 s0, s0, s1
	s_add_i32 s21, s0, 0xfffff400
	s_add_i32 s22, s0, 0xfffffc00
	v_readlane_b32 s0, v252, 32
	s_add_i32 s30, s21, s0
	s_add_i32 s0, s22, s0
	s_and_b32 s0, s0, 0xffffff80
	s_cmp_lt_i32 s61, 8
	s_cselect_b64 vcc, -1, 0
	v_or_b32_e32 v152, s0, v166
	s_and_b64 s[0:1], vcc, exec
	s_movk_i32 s0, 0x118
	s_cselect_b32 s0, s0, 0x120
	v_readlane_b32 s4, v253, 0
	v_readlane_b32 s5, v253, 1
	s_add_u32 s0, s4, s0
	s_addc_u32 s1, s5, 0
	s_load_dwordx2 s[0:1], s[0:1], 0x0
	v_or_b32_e32 v144, s30, v160
	v_cndmask_b32_e32 v144, v144, v152, vcc
	s_movk_i32 s4, 0x1200
	s_lshl_b32 s70, s20, 1
	s_waitcnt lgkmcnt(0)
	v_mov_b64_e32 v[148:149], s[0:1]
	v_mad_i64_i32 v[144:145], s[0:1], v144, s4, v[148:149]
	v_readlane_b32 s0, v252, 28
	v_lshl_add_u64 v[144:145], v[144:145], 0, s[70:71]
	s_lshl_b32 s42, s0, 1
	s_mov_b32 s43, s71
	v_lshl_add_u64 v[144:145], v[144:145], 0, s[42:43]
	v_lshl_add_u64 v[150:151], v[144:145], 0, v[176:177]
	v_cvt_pk_bf16_f32 v144, v124, v125
	v_cvt_pk_bf16_f32 v145, v126, v127
	v_cvt_pk_bf16_f32 v146, v120, v121
	v_cvt_pk_bf16_f32 v147, v122, v123
	global_store_dwordx4 v[150:151], v[144:147], off sc1
	s_nop 1
	v_cvt_pk_bf16_f32 v144, v108, v109
	v_cvt_pk_bf16_f32 v145, v110, v111
	v_cvt_pk_bf16_f32 v146, v104, v105
	v_cvt_pk_bf16_f32 v147, v106, v107
	global_store_dwordx4 v[150:151], v[144:147], off offset:64 sc1
	s_nop 1
	v_or_b32_e32 v144, 16, v152
	v_or_b32_e32 v145, s30, v163
	v_cndmask_b32_e32 v144, v145, v144, vcc
	v_mad_i64_i32 v[144:145], s[0:1], v144, s4, v[148:149]
	v_lshl_add_u64 v[144:145], v[144:145], 0, s[70:71]
	v_lshl_add_u64 v[144:145], v[144:145], 0, s[42:43]
	v_lshl_add_u64 v[150:151], v[144:145], 0, v[176:177]
	v_cvt_pk_bf16_f32 v144, v116, v117
	v_cvt_pk_bf16_f32 v145, v118, v119
	v_cvt_pk_bf16_f32 v146, v112, v113
	v_cvt_pk_bf16_f32 v147, v114, v115
	global_store_dwordx4 v[150:151], v[144:147], off sc1
	s_nop 1
	v_cvt_pk_bf16_f32 v144, v92, v93
	v_cvt_pk_bf16_f32 v145, v94, v95
	v_cvt_pk_bf16_f32 v146, v88, v89
	v_cvt_pk_bf16_f32 v147, v90, v91
	global_store_dwordx4 v[150:151], v[144:147], off offset:64 sc1
	s_nop 1
	v_or_b32_e32 v144, 32, v152
	v_or_b32_e32 v145, s30, v164
	v_cndmask_b32_e32 v144, v145, v144, vcc
	v_mad_i64_i32 v[144:145], s[0:1], v144, s4, v[148:149]
	v_lshl_add_u64 v[144:145], v[144:145], 0, s[70:71]
	v_lshl_add_u64 v[144:145], v[144:145], 0, s[42:43]
	v_lshl_add_u64 v[150:151], v[144:145], 0, v[176:177]
	v_cvt_pk_bf16_f32 v144, v100, v101
	v_cvt_pk_bf16_f32 v145, v102, v103
	v_cvt_pk_bf16_f32 v146, v96, v97
	v_cvt_pk_bf16_f32 v147, v98, v99
	global_store_dwordx4 v[150:151], v[144:147], off sc1
	s_nop 1
	v_cvt_pk_bf16_f32 v144, v76, v77
	v_cvt_pk_bf16_f32 v145, v78, v79
	v_cvt_pk_bf16_f32 v146, v72, v73
	v_cvt_pk_bf16_f32 v147, v74, v75
	global_store_dwordx4 v[150:151], v[144:147], off offset:64 sc1
	s_nop 1
	v_or_b32_e32 v144, 48, v152
	v_or_b32_e32 v145, s30, v165
	v_cndmask_b32_e32 v144, v145, v144, vcc
	v_mad_i64_i32 v[144:145], s[0:1], v144, s4, v[148:149]
	v_lshl_add_u64 v[144:145], v[144:145], 0, s[70:71]
	v_lshl_add_u64 v[144:145], v[144:145], 0, s[42:43]
	v_readlane_b32 s0, v252, 30
	v_lshl_add_u64 v[150:151], v[144:145], 0, v[176:177]
	v_cvt_pk_bf16_f32 v144, v84, v85
	v_cvt_pk_bf16_f32 v145, v86, v87
	v_cvt_pk_bf16_f32 v146, v80, v81
	v_cvt_pk_bf16_f32 v147, v82, v83
	s_add_i32 s22, s22, s0
	global_store_dwordx4 v[150:151], v[144:147], off sc1
	s_add_i32 s21, s21, s0
	s_and_b32 s0, s22, 0xffffff80
	v_cvt_pk_bf16_f32 v144, v68, v69
	v_cvt_pk_bf16_f32 v145, v70, v71
	v_cvt_pk_bf16_f32 v146, v64, v65
	v_cvt_pk_bf16_f32 v147, v66, v67
	global_store_dwordx4 v[150:151], v[144:147], off offset:64 sc1
	v_or_b32_e32 v152, s0, v167
	s_nop 0
	v_or_b32_e32 v144, s21, v160
	v_cndmask_b32_e32 v144, v144, v152, vcc
	v_mad_i64_i32 v[144:145], s[0:1], v144, s4, v[148:149]
	v_lshl_add_u64 v[144:145], v[144:145], 0, s[70:71]
	v_lshl_add_u64 v[144:145], v[144:145], 0, s[42:43]
	v_lshl_add_u64 v[150:151], v[144:145], 0, v[176:177]
	v_cvt_pk_bf16_f32 v144, v60, v61
	v_cvt_pk_bf16_f32 v145, v62, v63
	v_cvt_pk_bf16_f32 v146, v56, v57
	v_cvt_pk_bf16_f32 v147, v58, v59
	global_store_dwordx4 v[150:151], v[144:147], off sc1
	s_nop 1
	v_cvt_pk_bf16_f32 v144, v44, v45
	v_cvt_pk_bf16_f32 v145, v46, v47
	v_cvt_pk_bf16_f32 v146, v40, v41
	v_cvt_pk_bf16_f32 v147, v42, v43
	global_store_dwordx4 v[150:151], v[144:147], off offset:64 sc1
	s_nop 1
	v_or_b32_e32 v144, 16, v152
	v_or_b32_e32 v145, s21, v163
	v_cndmask_b32_e32 v144, v145, v144, vcc
	v_mad_i64_i32 v[144:145], s[0:1], v144, s4, v[148:149]
	v_lshl_add_u64 v[144:145], v[144:145], 0, s[70:71]
	v_lshl_add_u64 v[144:145], v[144:145], 0, s[42:43]
	v_lshl_add_u64 v[150:151], v[144:145], 0, v[176:177]
	v_cvt_pk_bf16_f32 v144, v52, v53
	v_cvt_pk_bf16_f32 v145, v54, v55
	v_cvt_pk_bf16_f32 v146, v48, v49
	v_cvt_pk_bf16_f32 v147, v50, v51
	global_store_dwordx4 v[150:151], v[144:147], off sc1
	s_nop 1
	v_cvt_pk_bf16_f32 v144, v28, v29
	v_cvt_pk_bf16_f32 v145, v30, v31
	v_cvt_pk_bf16_f32 v146, v24, v25
	v_cvt_pk_bf16_f32 v147, v26, v27
	global_store_dwordx4 v[150:151], v[144:147], off offset:64 sc1
	s_nop 1
	v_or_b32_e32 v144, 32, v152
	v_or_b32_e32 v145, s21, v164
	v_cndmask_b32_e32 v144, v145, v144, vcc
	v_mad_i64_i32 v[144:145], s[0:1], v144, s4, v[148:149]
	v_lshl_add_u64 v[144:145], v[144:145], 0, s[70:71]
	v_lshl_add_u64 v[144:145], v[144:145], 0, s[42:43]
	v_lshl_add_u64 v[150:151], v[144:145], 0, v[176:177]
	v_cvt_pk_bf16_f32 v144, v36, v37
	v_cvt_pk_bf16_f32 v145, v38, v39
	v_cvt_pk_bf16_f32 v146, v32, v33
	v_cvt_pk_bf16_f32 v147, v34, v35
	global_store_dwordx4 v[150:151], v[144:147], off sc1
	s_nop 1
	v_cvt_pk_bf16_f32 v144, v12, v13
	v_cvt_pk_bf16_f32 v145, v14, v15
	v_cvt_pk_bf16_f32 v146, v8, v9
	v_cvt_pk_bf16_f32 v147, v10, v11
	global_store_dwordx4 v[150:151], v[144:147], off offset:64 sc1
	s_nop 1
	v_or_b32_e32 v144, 48, v152
	v_or_b32_e32 v145, s21, v165
	v_cndmask_b32_e32 v144, v145, v144, vcc
	v_mad_i64_i32 v[144:145], s[0:1], v144, s4, v[148:149]
	v_lshl_add_u64 v[144:145], v[144:145], 0, s[70:71]
	v_lshl_add_u64 v[144:145], v[144:145], 0, s[42:43]
	v_lshl_add_u64 v[148:149], v[144:145], 0, v[176:177]
	v_cvt_pk_bf16_f32 v144, v20, v21
	v_cvt_pk_bf16_f32 v145, v22, v23
	v_cvt_pk_bf16_f32 v146, v16, v17
	v_cvt_pk_bf16_f32 v147, v18, v19
	global_store_dwordx4 v[148:149], v[144:147], off sc1
	s_nop 1
	v_cvt_pk_bf16_f32 v144, v4, v5
	v_cvt_pk_bf16_f32 v145, v6, v7
	v_cvt_pk_bf16_f32 v146, v0, v1
	v_cvt_pk_bf16_f32 v147, v2, v3
	global_store_dwordx4 v[148:149], v[144:147], off offset:64 sc1
	s_cbranch_execz .LBB0_652
	s_andn2_b64 vcc, exec, s[58:59]
	s_mov_b64 s[0:1], -1
	s_cbranch_vccnz .LBB0_622
	s_branch .LBB0_670

.LBB0_669:
	s_lshl_b32 s20, s61, 8
	s_cmp_lt_u32 s61, 12
	s_movk_i32 s0, 0xfe00
	s_cselect_b32 s21, s0, 0xfffffc00
	s_and_b64 s[0:1], s[62:63], exec
	s_cselect_b32 s0, 0, s21
	s_ashr_i32 s61, s60, 31
	s_add_i32 s0, s0, s20
	s_lshl_b64 s[20:21], s[60:61], 8
	v_lshl_add_u64 v[144:145], v[138:139], 0, s[20:21]
	v_readlane_b32 s20, v253, 0
	v_readlane_b32 s21, v253, 1
	s_mov_b32 s30, s7
	s_mov_b32 s22, s6
	s_load_dwordx16 s[4:19], s[20:21], 0xf0
	v_cvt_pk_bf16_f32 v124, v124, v125
	v_cvt_pk_bf16_f32 v125, v126, v127
	v_cvt_pk_bf16_f32 v126, v120, v121
	s_waitcnt lgkmcnt(0)
	s_movk_i32 s4, 0x3c00
	v_mov_b64_e32 v[120:121], s[12:13]
	v_mad_u64_u32 v[120:121], s[20:21], v144, s4, v[120:121]
	v_cvt_pk_bf16_f32 v127, v122, v123
	v_mov_b32_e32 v122, v121
	v_mad_u64_u32 v[122:123], s[20:21], v145, s4, v[122:123]
	s_ashr_i32 s1, s0, 31
	v_mov_b32_e32 v121, v122
	v_lshl_add_u64 v[120:121], s[0:1], 1, v[120:121]
	v_readlane_b32 s0, v252, 28
	s_lshl_b32 s70, s0, 1
	v_lshl_add_u64 v[120:121], v[120:121], 0, s[70:71]
	v_lshl_add_u64 v[120:121], v[120:121], 0, v[176:177]
	v_cvt_pk_bf16_f32 v108, v108, v109
	v_cvt_pk_bf16_f32 v109, v110, v111
	v_cvt_pk_bf16_f32 v110, v104, v105
	v_cvt_pk_bf16_f32 v111, v106, v107
	s_mov_b64 s[0:1], 0x3c000
	global_store_dwordx4 v[120:121], v[108:111], off offset:64 sc1
	v_cvt_pk_bf16_f32 v92, v92, v93
	v_cvt_pk_bf16_f32 v93, v94, v95
	v_lshl_add_u64 v[108:109], v[120:121], 0, s[0:1]
	s_mov_b32 s0, 0x3c000
	v_add_co_u32_e32 v110, vcc, s0, v120
	v_cvt_pk_bf16_f32 v94, v88, v89
	v_cvt_pk_bf16_f32 v95, v90, v91
	s_mov_b64 s[0:1], 0x78000
	v_addc_co_u32_e32 v111, vcc, 0, v121, vcc
	global_store_dwordx4 v[108:109], v[92:95], off offset:64 sc1
	v_cvt_pk_bf16_f32 v76, v76, v77
	v_cvt_pk_bf16_f32 v77, v78, v79
	v_lshl_add_u64 v[92:93], v[120:121], 0, s[0:1]
	s_mov_b32 s0, 0x78000
	v_add_co_u32_e32 v94, vcc, s0, v120
	v_cvt_pk_bf16_f32 v78, v72, v73
	v_cvt_pk_bf16_f32 v79, v74, v75
	s_mov_b64 s[0:1], 0xb4000
	v_addc_co_u32_e32 v95, vcc, 0, v121, vcc
	global_store_dwordx4 v[92:93], v[76:79], off offset:64 sc1
	v_cvt_pk_bf16_f32 v60, v60, v61
	v_cvt_pk_bf16_f32 v61, v62, v63
	v_lshl_add_u64 v[76:77], v[120:121], 0, s[0:1]
	s_mov_b32 s0, 0xb4000
	v_add_co_u32_e32 v78, vcc, s0, v120
	s_mov_b64 s[0:1], 0x1e0000
	s_nop 0
	v_addc_co_u32_e32 v79, vcc, 0, v121, vcc
	v_cvt_pk_bf16_f32 v62, v56, v57
	v_lshl_add_u64 v[56:57], v[120:121], 0, s[0:1]
	s_mov_b32 s0, 0x1e0000
	v_cvt_pk_bf16_f32 v63, v58, v59
	v_add_co_u32_e32 v58, vcc, s0, v120
	v_cvt_pk_bf16_f32 v44, v44, v45
	v_cvt_pk_bf16_f32 v45, v46, v47
	v_cvt_pk_bf16_f32 v46, v40, v41
	v_cvt_pk_bf16_f32 v47, v42, v43
	s_mov_b64 s[0:1], 0x21c000
	v_addc_co_u32_e32 v59, vcc, 0, v121, vcc
	global_store_dwordx4 v[56:57], v[44:47], off offset:64 sc1
	v_cvt_pk_bf16_f32 v28, v28, v29
	v_cvt_pk_bf16_f32 v29, v30, v31
	v_lshl_add_u64 v[44:45], v[120:121], 0, s[0:1]
	s_mov_b32 s0, 0x21c000
	v_add_co_u32_e32 v46, vcc, s0, v120
	v_cvt_pk_bf16_f32 v30, v24, v25
	v_cvt_pk_bf16_f32 v31, v26, v27
	s_mov_b64 s[0:1], 0x258000
	v_addc_co_u32_e32 v47, vcc, 0, v121, vcc
	global_store_dwordx4 v[44:45], v[28:31], off offset:64 sc1
	v_cvt_pk_bf16_f32 v12, v12, v13
	v_cvt_pk_bf16_f32 v13, v14, v15
	v_lshl_add_u64 v[28:29], v[120:121], 0, s[0:1]
	s_mov_b32 s0, 0x258000
	v_add_co_u32_e32 v30, vcc, s0, v120
	v_cvt_pk_bf16_f32 v14, v8, v9
	v_cvt_pk_bf16_f32 v15, v10, v11
	s_mov_b64 s[0:1], 0x294000
	v_addc_co_u32_e32 v31, vcc, 0, v121, vcc
	global_store_dwordx4 v[28:29], v[12:15], off offset:64 sc1
	v_cvt_pk_bf16_f32 v104, v116, v117
	v_cvt_pk_bf16_f32 v105, v118, v119
	v_lshl_add_u64 v[12:13], v[120:121], 0, s[0:1]
	s_mov_b32 s0, 0x294000
	v_add_co_u32_e32 v14, vcc, s0, v120
	v_cvt_pk_bf16_f32 v106, v112, v113
	v_cvt_pk_bf16_f32 v107, v114, v115
	v_cvt_pk_bf16_f32 v88, v100, v101
	v_cvt_pk_bf16_f32 v89, v102, v103
	v_cvt_pk_bf16_f32 v90, v96, v97
	v_cvt_pk_bf16_f32 v91, v98, v99
	v_cvt_pk_bf16_f32 v72, v84, v85
	v_cvt_pk_bf16_f32 v73, v86, v87
	v_cvt_pk_bf16_f32 v74, v80, v81
	v_cvt_pk_bf16_f32 v75, v82, v83
	v_cvt_pk_bf16_f32 v68, v68, v69
	v_cvt_pk_bf16_f32 v69, v70, v71
	v_cvt_pk_bf16_f32 v70, v64, v65
	v_cvt_pk_bf16_f32 v71, v66, v67
	v_cvt_pk_bf16_f32 v40, v52, v53
	v_cvt_pk_bf16_f32 v41, v54, v55
	v_cvt_pk_bf16_f32 v42, v48, v49
	v_cvt_pk_bf16_f32 v43, v50, v51
	v_cvt_pk_bf16_f32 v24, v36, v37
	v_cvt_pk_bf16_f32 v25, v38, v39
	v_cvt_pk_bf16_f32 v26, v32, v33
	v_cvt_pk_bf16_f32 v27, v34, v35
	v_cvt_pk_bf16_f32 v8, v20, v21
	v_cvt_pk_bf16_f32 v9, v22, v23
	v_cvt_pk_bf16_f32 v10, v16, v17
	v_cvt_pk_bf16_f32 v11, v18, v19
	v_addc_co_u32_e32 v15, vcc, 0, v121, vcc
	v_cvt_pk_bf16_f32 v4, v4, v5
	v_cvt_pk_bf16_f32 v5, v6, v7
	v_cvt_pk_bf16_f32 v6, v0, v1
	v_cvt_pk_bf16_f32 v7, v2, v3
	s_mov_b32 s6, s22
	s_mov_b32 s7, s30
	global_store_dwordx4 v[120:121], v[124:127], off sc1
	global_store_dwordx4 v[110:111], v[104:107], off sc1
	global_store_dwordx4 v[94:95], v[88:91], off sc1
	global_store_dwordx4 v[78:79], v[72:75], off sc1
	global_store_dwordx4 v[76:77], v[68:71], off offset:64 sc1
	global_store_dwordx4 v[58:59], v[60:63], off sc1
	global_store_dwordx4 v[46:47], v[40:43], off sc1
	global_store_dwordx4 v[30:31], v[24:27], off sc1
	global_store_dwordx4 v[14:15], v[8:11], off sc1
	global_store_dwordx4 v[12:13], v[4:7], off offset:64 sc1
	s_andn2_b64 vcc, exec, s[58:59]
	s_mov_b64 s[0:1], -1
	s_cbranch_vccnz .LBB0_622
